# v48 + nt on P5 regular-epilogue HID stores
# speedup vs baseline: 1.0086x; 1.0031x over previous
.LBB0_2298:
	s_lshl_b32 s5, s41, 10
	s_and_b32 s5, s5, 0x400
	v_add_u32_e32 v163, s5, v129
	ds_read_b32 v164, v163
	v_lshl_add_u32 v150, s42, 8, v156
	v_ashrrev_i32_e32 v151, 31, v150
	v_lshlrev_b64 v[152:153], 15, v[150:151]
	v_lshl_add_u32 v148, s40, 8, v158
	s_waitcnt lgkmcnt(0)
	v_fmamk_f32 v151, v164, 0x39800000, v162
	v_rsq_f32_e32 v168, v151
	v_ashrrev_i32_e32 v149, 31, v148
	v_lshl_add_u64 v[164:165], s[2:3], 0, v[152:153]
	v_lshlrev_b64 v[152:153], 1, v[148:149]
	v_lshl_add_u64 v[148:149], v[164:165], 0, v[152:153]
	v_pk_mul_f32 v[164:165], v[114:115], v[168:169] op_sel_hi:[1,0]
	v_pk_mul_f32 v[166:167], v[112:113], v[168:169] op_sel_hi:[1,0]
	v_pk_mul_f32 v[172:173], v[116:117], v[168:169] op_sel_hi:[1,0]
	v_pk_mul_f32 v[170:171], v[118:119], v[168:169] op_sel_hi:[1,0]
	v_max_f32_e32 v166, 0, v166
	v_max_f32_e32 v172, 0, v172
	v_max_f32_e32 v167, 0, v167
	v_max_f32_e32 v173, 0, v173
	v_max_f32_e32 v164, 0, v164
	v_max_f32_e32 v165, 0, v165
	v_max_f32_e32 v170, 0, v170
	v_max_f32_e32 v171, 0, v171
	v_pk_mul_f32 v[174:175], v[164:165], v[164:165]
	v_pk_mul_f32 v[164:165], v[166:167], v[166:167]
	v_pk_mul_f32 v[166:167], v[172:173], v[172:173]
	v_pk_mul_f32 v[170:171], v[170:171], v[170:171]
	v_cvt_pk_bf16_f32 v164, v164, v165
	v_cvt_pk_bf16_f32 v165, v174, v175
	v_cvt_pk_bf16_f32 v166, v166, v167
	s_mov_b32 s5, 0x400000
	v_cvt_pk_bf16_f32 v167, v170, v171
	global_store_dwordx4 v[148:149], v[164:167], off nt
	v_pk_mul_f32 v[170:171], v[122:123], v[168:169] op_sel_hi:[1,0]
	s_mov_b64 s[40:41], 0x400000
	v_pk_mul_f32 v[164:165], v[126:127], v[168:169] op_sel_hi:[1,0]
	v_pk_mul_f32 v[166:167], v[124:125], v[168:169] op_sel_hi:[1,0]
	v_pk_mul_f32 v[168:169], v[120:121], v[168:169] op_sel_hi:[1,0]
	v_max_f32_e32 v166, 0, v166
	v_max_f32_e32 v168, 0, v168
	v_max_f32_e32 v167, 0, v167
	v_max_f32_e32 v169, 0, v169
	v_max_f32_e32 v164, 0, v164
	v_max_f32_e32 v165, 0, v165
	v_max_f32_e32 v170, 0, v170
	v_max_f32_e32 v171, 0, v171
	v_pk_mul_f32 v[172:173], v[164:165], v[164:165]
	v_pk_mul_f32 v[164:165], v[166:167], v[166:167]
	v_pk_mul_f32 v[166:167], v[168:169], v[168:169]
	v_pk_mul_f32 v[170:171], v[170:171], v[170:171]
	v_cvt_pk_bf16_f32 v164, v164, v165
	v_cvt_pk_bf16_f32 v165, v172, v173
	v_cvt_pk_bf16_f32 v166, v166, v167
	s_nop 0
	v_cvt_pk_bf16_f32 v167, v170, v171
	ds_read_b32 v151, v163 offset:64
	global_store_dwordx4 v[148:149], v[164:167], off offset:256 nt
	s_waitcnt lgkmcnt(0)
	v_fmamk_f32 v151, v151, 0x39800000, v162
	v_or_b32_e32 v164, 16, v150
	v_rsq_f32_e32 v168, v151
	v_ashrrev_i32_e32 v165, 31, v164
	v_lshlrev_b64 v[164:165], 15, v[164:165]
	v_lshl_add_u64 v[164:165], s[2:3], 0, v[164:165]
	v_lshl_add_u64 v[170:171], v[164:165], 0, v[152:153]
	v_pk_mul_f32 v[164:165], v[102:103], v[168:169] op_sel_hi:[1,0]
	v_pk_mul_f32 v[166:167], v[100:101], v[168:169] op_sel_hi:[1,0]
	v_pk_mul_f32 v[174:175], v[96:97], v[168:169] op_sel_hi:[1,0]
	v_pk_mul_f32 v[172:173], v[98:99], v[168:169] op_sel_hi:[1,0]
	v_max_f32_e32 v166, 0, v166
	v_max_f32_e32 v174, 0, v174
	v_max_f32_e32 v167, 0, v167
	v_max_f32_e32 v175, 0, v175
	v_max_f32_e32 v164, 0, v164
	v_max_f32_e32 v165, 0, v165
	v_max_f32_e32 v172, 0, v172
	v_max_f32_e32 v173, 0, v173
	v_pk_mul_f32 v[176:177], v[164:165], v[164:165]
	v_pk_mul_f32 v[164:165], v[166:167], v[166:167]
	v_pk_mul_f32 v[166:167], v[174:175], v[174:175]
	v_pk_mul_f32 v[172:173], v[172:173], v[172:173]
	v_cvt_pk_bf16_f32 v164, v164, v165
	v_cvt_pk_bf16_f32 v165, v176, v177
	v_cvt_pk_bf16_f32 v166, v166, v167
	s_nop 0
	v_cvt_pk_bf16_f32 v167, v172, v173
	global_store_dwordx4 v[170:171], v[164:167], off nt
	v_pk_mul_f32 v[172:173], v[106:107], v[168:169] op_sel_hi:[1,0]
	s_nop 0
	v_pk_mul_f32 v[164:165], v[110:111], v[168:169] op_sel_hi:[1,0]
	v_pk_mul_f32 v[166:167], v[108:109], v[168:169] op_sel_hi:[1,0]
	v_pk_mul_f32 v[168:169], v[104:105], v[168:169] op_sel_hi:[1,0]
	v_max_f32_e32 v166, 0, v166
	v_max_f32_e32 v168, 0, v168
	v_max_f32_e32 v167, 0, v167
	v_max_f32_e32 v169, 0, v169
	v_max_f32_e32 v164, 0, v164
	v_max_f32_e32 v165, 0, v165
	v_max_f32_e32 v172, 0, v172
	v_max_f32_e32 v173, 0, v173
	v_pk_mul_f32 v[174:175], v[164:165], v[164:165]
	v_pk_mul_f32 v[164:165], v[166:167], v[166:167]
	v_pk_mul_f32 v[166:167], v[168:169], v[168:169]
	v_pk_mul_f32 v[172:173], v[172:173], v[172:173]
	v_cvt_pk_bf16_f32 v164, v164, v165
	v_cvt_pk_bf16_f32 v165, v174, v175
	v_cvt_pk_bf16_f32 v166, v166, v167
	s_nop 0
	v_cvt_pk_bf16_f32 v167, v172, v173
	ds_read_b32 v151, v163 offset:128
	global_store_dwordx4 v[170:171], v[164:167], off offset:256 nt
	s_waitcnt lgkmcnt(0)
	v_fmamk_f32 v151, v151, 0x39800000, v162
	v_or_b32_e32 v164, 32, v150
	v_rsq_f32_e32 v168, v151
	v_ashrrev_i32_e32 v165, 31, v164
	v_lshlrev_b64 v[164:165], 15, v[164:165]
	v_lshl_add_u64 v[164:165], s[2:3], 0, v[164:165]
	v_lshl_add_u64 v[170:171], v[164:165], 0, v[152:153]
	v_pk_mul_f32 v[164:165], v[86:87], v[168:169] op_sel_hi:[1,0]
	v_pk_mul_f32 v[166:167], v[84:85], v[168:169] op_sel_hi:[1,0]
	v_pk_mul_f32 v[174:175], v[80:81], v[168:169] op_sel_hi:[1,0]
	v_pk_mul_f32 v[172:173], v[82:83], v[168:169] op_sel_hi:[1,0]
	v_max_f32_e32 v166, 0, v166
	v_max_f32_e32 v174, 0, v174
	v_max_f32_e32 v167, 0, v167
	v_max_f32_e32 v175, 0, v175
	v_max_f32_e32 v164, 0, v164
	v_max_f32_e32 v165, 0, v165
	v_max_f32_e32 v172, 0, v172
	v_max_f32_e32 v173, 0, v173
	v_pk_mul_f32 v[176:177], v[164:165], v[164:165]
	v_pk_mul_f32 v[164:165], v[166:167], v[166:167]
	v_pk_mul_f32 v[166:167], v[174:175], v[174:175]
	v_pk_mul_f32 v[172:173], v[172:173], v[172:173]
	v_cvt_pk_bf16_f32 v164, v164, v165
	v_cvt_pk_bf16_f32 v165, v176, v177
	v_cvt_pk_bf16_f32 v166, v166, v167
	v_or_b32_e32 v150, 48, v150
	v_cvt_pk_bf16_f32 v167, v172, v173
	global_store_dwordx4 v[170:171], v[164:167], off nt
	v_pk_mul_f32 v[172:173], v[90:91], v[168:169] op_sel_hi:[1,0]
	v_ashrrev_i32_e32 v151, 31, v150
	v_pk_mul_f32 v[164:165], v[94:95], v[168:169] op_sel_hi:[1,0]
	v_pk_mul_f32 v[166:167], v[92:93], v[168:169] op_sel_hi:[1,0]
	v_pk_mul_f32 v[168:169], v[88:89], v[168:169] op_sel_hi:[1,0]
	v_max_f32_e32 v166, 0, v166
	v_max_f32_e32 v168, 0, v168
	v_max_f32_e32 v167, 0, v167
	v_max_f32_e32 v169, 0, v169
	v_max_f32_e32 v164, 0, v164
	v_max_f32_e32 v165, 0, v165
	v_max_f32_e32 v172, 0, v172
	v_max_f32_e32 v173, 0, v173
	v_pk_mul_f32 v[174:175], v[164:165], v[164:165]
	v_pk_mul_f32 v[164:165], v[166:167], v[166:167]
	v_pk_mul_f32 v[166:167], v[168:169], v[168:169]
	v_pk_mul_f32 v[172:173], v[172:173], v[172:173]
	v_cvt_pk_bf16_f32 v164, v164, v165
	v_cvt_pk_bf16_f32 v165, v174, v175
	v_cvt_pk_bf16_f32 v166, v166, v167
	v_lshlrev_b64 v[150:151], 15, v[150:151]
	v_cvt_pk_bf16_f32 v167, v172, v173
	ds_read_b32 v168, v163 offset:192
	global_store_dwordx4 v[170:171], v[164:167], off offset:256 nt
	v_lshl_add_u64 v[150:151], s[2:3], 0, v[150:151]
	s_nop 0
	v_lshl_add_u64 v[166:167], v[150:151], 0, v[152:153]
	s_waitcnt lgkmcnt(0)
	v_fmamk_f32 v164, v168, 0x39800000, v162
	v_rsq_f32_e32 v164, v164
	s_nop 0
	v_pk_mul_f32 v[150:151], v[54:55], v[164:165] op_sel_hi:[1,0]
	v_pk_mul_f32 v[152:153], v[52:53], v[164:165] op_sel_hi:[1,0]
	v_pk_mul_f32 v[170:171], v[48:49], v[164:165] op_sel_hi:[1,0]
	v_pk_mul_f32 v[168:169], v[50:51], v[164:165] op_sel_hi:[1,0]
	v_max_f32_e32 v152, 0, v152
	v_max_f32_e32 v170, 0, v170
	v_max_f32_e32 v153, 0, v153
	v_max_f32_e32 v171, 0, v171
	v_max_f32_e32 v150, 0, v150
	v_max_f32_e32 v151, 0, v151
	v_max_f32_e32 v168, 0, v168
	v_max_f32_e32 v169, 0, v169
	v_pk_mul_f32 v[172:173], v[150:151], v[150:151]
	v_pk_mul_f32 v[150:151], v[152:153], v[152:153]
	v_pk_mul_f32 v[152:153], v[170:171], v[170:171]
	v_pk_mul_f32 v[168:169], v[168:169], v[168:169]
	v_cvt_pk_bf16_f32 v150, v150, v151
	v_cvt_pk_bf16_f32 v151, v172, v173
	v_cvt_pk_bf16_f32 v152, v152, v153
	s_nop 0
	v_cvt_pk_bf16_f32 v153, v168, v169
	global_store_dwordx4 v[166:167], v[150:153], off nt
	v_pk_mul_f32 v[168:169], v[66:67], v[164:165] op_sel_hi:[1,0]
	s_nop 0
	v_pk_mul_f32 v[150:151], v[70:71], v[164:165] op_sel_hi:[1,0]
	v_pk_mul_f32 v[152:153], v[68:69], v[164:165] op_sel_hi:[1,0]
	v_pk_mul_f32 v[164:165], v[64:65], v[164:165] op_sel_hi:[1,0]
	v_max_f32_e32 v152, 0, v152
	v_max_f32_e32 v164, 0, v164
	v_max_f32_e32 v153, 0, v153
	v_max_f32_e32 v165, 0, v165
	v_max_f32_e32 v150, 0, v150
	v_max_f32_e32 v151, 0, v151
	v_max_f32_e32 v168, 0, v168
	v_max_f32_e32 v169, 0, v169
	v_pk_mul_f32 v[170:171], v[150:151], v[150:151]
	v_pk_mul_f32 v[150:151], v[152:153], v[152:153]
	v_pk_mul_f32 v[152:153], v[164:165], v[164:165]
	v_pk_mul_f32 v[168:169], v[168:169], v[168:169]
	v_cvt_pk_bf16_f32 v150, v150, v151
	v_cvt_pk_bf16_f32 v151, v170, v171
	v_cvt_pk_bf16_f32 v152, v152, v153
	s_nop 0
	v_cvt_pk_bf16_f32 v153, v168, v169
	ds_read_b32 v164, v163 offset:512
	global_store_dwordx4 v[166:167], v[150:153], off offset:256 nt
	s_waitcnt lgkmcnt(0)
	v_fmamk_f32 v164, v164, 0x39800000, v162
	v_rsq_f32_e32 v164, v164
	s_nop 0
	v_pk_mul_f32 v[150:151], v[62:63], v[164:165] op_sel_hi:[1,0]
	v_pk_mul_f32 v[152:153], v[60:61], v[164:165] op_sel_hi:[1,0]
	v_pk_mul_f32 v[166:167], v[58:59], v[164:165] op_sel_hi:[1,0]
	v_pk_mul_f32 v[168:169], v[56:57], v[164:165] op_sel_hi:[1,0]
	v_max_f32_e32 v152, 0, v152
	v_max_f32_e32 v168, 0, v168
	v_max_f32_e32 v153, 0, v153
	v_max_f32_e32 v169, 0, v169
	v_max_f32_e32 v150, 0, v150
	v_max_f32_e32 v166, 0, v166
	v_max_f32_e32 v151, 0, v151
	v_max_f32_e32 v167, 0, v167
	v_pk_mul_f32 v[170:171], v[150:151], v[150:151]
	v_pk_mul_f32 v[150:151], v[152:153], v[152:153]
	v_pk_mul_f32 v[166:167], v[166:167], v[166:167]
	v_pk_mul_f32 v[152:153], v[168:169], v[168:169]
	v_cvt_pk_bf16_f32 v150, v150, v151
	v_cvt_pk_bf16_f32 v151, v170, v171
	s_nop 0
	v_cvt_pk_bf16_f32 v152, v152, v153
	v_cvt_pk_bf16_f32 v153, v166, v167
	v_add_co_u32_e32 v166, vcc, s5, v148
	s_mov_b32 s5, 0x480000
	s_nop 0
	v_addc_co_u32_e32 v167, vcc, 0, v149, vcc
	global_store_dwordx4 v[166:167], v[150:153], off nt
	v_pk_mul_f32 v[166:167], v[74:75], v[164:165] op_sel_hi:[1,0]
	s_nop 0
	v_pk_mul_f32 v[150:151], v[78:79], v[164:165] op_sel_hi:[1,0]
	v_pk_mul_f32 v[152:153], v[76:77], v[164:165] op_sel_hi:[1,0]
	v_pk_mul_f32 v[164:165], v[72:73], v[164:165] op_sel_hi:[1,0]
	v_max_f32_e32 v152, 0, v152
	v_max_f32_e32 v164, 0, v164
	v_max_f32_e32 v153, 0, v153
	v_max_f32_e32 v165, 0, v165
	v_max_f32_e32 v150, 0, v150
	v_max_f32_e32 v151, 0, v151
	v_max_f32_e32 v166, 0, v166
	v_max_f32_e32 v167, 0, v167
	v_pk_mul_f32 v[168:169], v[150:151], v[150:151]
	v_pk_mul_f32 v[150:151], v[152:153], v[152:153]
	v_pk_mul_f32 v[152:153], v[164:165], v[164:165]
	v_pk_mul_f32 v[166:167], v[166:167], v[166:167]
	v_cvt_pk_bf16_f32 v150, v150, v151
	v_cvt_pk_bf16_f32 v151, v168, v169
	v_cvt_pk_bf16_f32 v152, v152, v153
	s_nop 0
	v_cvt_pk_bf16_f32 v153, v166, v167
	ds_read_b32 v164, v163 offset:576
	v_lshl_add_u64 v[166:167], v[148:149], 0, s[40:41]
	global_store_dwordx4 v[166:167], v[150:153], off offset:256 nt
	s_mov_b64 s[40:41], 0x480000
	s_waitcnt lgkmcnt(0)
	v_fmamk_f32 v164, v164, 0x39800000, v162
	v_rsq_f32_e32 v164, v164
	s_nop 0
	v_pk_mul_f32 v[150:151], v[38:39], v[164:165] op_sel_hi:[1,0]
	v_pk_mul_f32 v[152:153], v[36:37], v[164:165] op_sel_hi:[1,0]
	v_pk_mul_f32 v[166:167], v[34:35], v[164:165] op_sel_hi:[1,0]
	v_pk_mul_f32 v[168:169], v[32:33], v[164:165] op_sel_hi:[1,0]
	v_max_f32_e32 v152, 0, v152
	v_max_f32_e32 v168, 0, v168
	v_max_f32_e32 v153, 0, v153
	v_max_f32_e32 v169, 0, v169
	v_max_f32_e32 v150, 0, v150
	v_max_f32_e32 v166, 0, v166
	v_max_f32_e32 v151, 0, v151
	v_max_f32_e32 v167, 0, v167
	v_pk_mul_f32 v[170:171], v[150:151], v[150:151]
	v_pk_mul_f32 v[150:151], v[152:153], v[152:153]
	v_pk_mul_f32 v[166:167], v[166:167], v[166:167]
	v_pk_mul_f32 v[152:153], v[168:169], v[168:169]
	v_cvt_pk_bf16_f32 v150, v150, v151
	v_cvt_pk_bf16_f32 v151, v170, v171
	s_nop 0
	v_cvt_pk_bf16_f32 v152, v152, v153
	v_cvt_pk_bf16_f32 v153, v166, v167
	v_add_co_u32_e32 v166, vcc, s5, v148
	s_mov_b32 s5, 0x500000
	s_nop 0
	v_addc_co_u32_e32 v167, vcc, 0, v149, vcc
	global_store_dwordx4 v[166:167], v[150:153], off nt
	v_pk_mul_f32 v[166:167], v[42:43], v[164:165] op_sel_hi:[1,0]
	s_nop 0
	v_pk_mul_f32 v[150:151], v[46:47], v[164:165] op_sel_hi:[1,0]
	v_pk_mul_f32 v[152:153], v[44:45], v[164:165] op_sel_hi:[1,0]
	v_pk_mul_f32 v[164:165], v[40:41], v[164:165] op_sel_hi:[1,0]
	v_max_f32_e32 v152, 0, v152
	v_max_f32_e32 v164, 0, v164
	v_max_f32_e32 v153, 0, v153
	v_max_f32_e32 v165, 0, v165
	v_max_f32_e32 v150, 0, v150
	v_max_f32_e32 v151, 0, v151
	v_max_f32_e32 v166, 0, v166
	v_max_f32_e32 v167, 0, v167
	v_pk_mul_f32 v[168:169], v[150:151], v[150:151]
	v_pk_mul_f32 v[150:151], v[152:153], v[152:153]
	v_pk_mul_f32 v[152:153], v[164:165], v[164:165]
	v_pk_mul_f32 v[166:167], v[166:167], v[166:167]
	v_cvt_pk_bf16_f32 v150, v150, v151
	v_cvt_pk_bf16_f32 v151, v168, v169
	v_cvt_pk_bf16_f32 v152, v152, v153
	s_nop 0
	v_cvt_pk_bf16_f32 v153, v166, v167
	ds_read_b32 v164, v163 offset:640
	v_lshl_add_u64 v[166:167], v[148:149], 0, s[40:41]
	global_store_dwordx4 v[166:167], v[150:153], off offset:256 nt
	s_mov_b64 s[40:41], 0x500000
	s_waitcnt lgkmcnt(0)
	v_fmamk_f32 v164, v164, 0x39800000, v162
	v_rsq_f32_e32 v164, v164
	s_nop 0
	v_pk_mul_f32 v[150:151], v[22:23], v[164:165] op_sel_hi:[1,0]
	v_pk_mul_f32 v[152:153], v[20:21], v[164:165] op_sel_hi:[1,0]
	v_pk_mul_f32 v[166:167], v[18:19], v[164:165] op_sel_hi:[1,0]
	v_pk_mul_f32 v[168:169], v[16:17], v[164:165] op_sel_hi:[1,0]
	v_max_f32_e32 v152, 0, v152
	v_max_f32_e32 v168, 0, v168
	v_max_f32_e32 v153, 0, v153
	v_max_f32_e32 v169, 0, v169
	v_max_f32_e32 v150, 0, v150
	v_max_f32_e32 v166, 0, v166
	v_max_f32_e32 v151, 0, v151
	v_max_f32_e32 v167, 0, v167
	v_pk_mul_f32 v[170:171], v[150:151], v[150:151]
	v_pk_mul_f32 v[150:151], v[152:153], v[152:153]
	v_pk_mul_f32 v[166:167], v[166:167], v[166:167]
	v_pk_mul_f32 v[152:153], v[168:169], v[168:169]
	v_cvt_pk_bf16_f32 v150, v150, v151
	v_cvt_pk_bf16_f32 v151, v170, v171
	s_nop 0
	v_cvt_pk_bf16_f32 v152, v152, v153
	v_cvt_pk_bf16_f32 v153, v166, v167
	v_add_co_u32_e32 v166, vcc, s5, v148
	s_mov_b32 s5, 0x580000
	s_nop 0
	v_addc_co_u32_e32 v167, vcc, 0, v149, vcc
	global_store_dwordx4 v[166:167], v[150:153], off nt
	v_pk_mul_f32 v[166:167], v[26:27], v[164:165] op_sel_hi:[1,0]
	s_nop 0
	v_pk_mul_f32 v[150:151], v[30:31], v[164:165] op_sel_hi:[1,0]
	v_pk_mul_f32 v[152:153], v[28:29], v[164:165] op_sel_hi:[1,0]
	v_pk_mul_f32 v[164:165], v[24:25], v[164:165] op_sel_hi:[1,0]
	v_max_f32_e32 v152, 0, v152
	v_max_f32_e32 v164, 0, v164
	v_max_f32_e32 v153, 0, v153
	v_max_f32_e32 v165, 0, v165
	v_max_f32_e32 v150, 0, v150
	v_max_f32_e32 v151, 0, v151
	v_max_f32_e32 v166, 0, v166
	v_max_f32_e32 v167, 0, v167
	v_pk_mul_f32 v[168:169], v[150:151], v[150:151]
	v_pk_mul_f32 v[150:151], v[152:153], v[152:153]
	v_pk_mul_f32 v[152:153], v[164:165], v[164:165]
	v_pk_mul_f32 v[166:167], v[166:167], v[166:167]
	v_cvt_pk_bf16_f32 v150, v150, v151
	v_cvt_pk_bf16_f32 v151, v168, v169
	v_cvt_pk_bf16_f32 v152, v152, v153
	s_nop 0
	v_cvt_pk_bf16_f32 v153, v166, v167
	ds_read_b32 v163, v163 offset:704
	v_lshl_add_u64 v[166:167], v[148:149], 0, s[40:41]
	global_store_dwordx4 v[166:167], v[150:153], off offset:256 nt
	s_mov_b64 s[40:41], 0x580000
	v_lshl_add_u64 v[166:167], v[148:149], 0, s[40:41]
	s_waitcnt lgkmcnt(0)
	v_fmamk_f32 v163, v163, 0x39800000, v162
	v_rsq_f32_e32 v164, v163
	v_add_co_u32_e32 v148, vcc, s5, v148
	v_pk_mul_f32 v[150:151], v[6:7], v[164:165] op_sel_hi:[1,0]
	v_pk_mul_f32 v[152:153], v[4:5], v[164:165] op_sel_hi:[1,0]
	v_pk_mul_f32 v[170:171], v[0:1], v[164:165] op_sel_hi:[1,0]
	v_pk_mul_f32 v[168:169], v[2:3], v[164:165] op_sel_hi:[1,0]
	v_max_f32_e32 v152, 0, v152
	v_max_f32_e32 v170, 0, v170
	v_max_f32_e32 v153, 0, v153
	v_max_f32_e32 v171, 0, v171
	v_max_f32_e32 v150, 0, v150
	v_max_f32_e32 v151, 0, v151
	v_max_f32_e32 v168, 0, v168
	v_max_f32_e32 v169, 0, v169
	v_pk_mul_f32 v[172:173], v[150:151], v[150:151]
	v_pk_mul_f32 v[150:151], v[152:153], v[152:153]
	v_pk_mul_f32 v[152:153], v[170:171], v[170:171]
	v_pk_mul_f32 v[168:169], v[168:169], v[168:169]
	v_cvt_pk_bf16_f32 v150, v150, v151
	v_cvt_pk_bf16_f32 v151, v172, v173
	v_cvt_pk_bf16_f32 v152, v152, v153
	v_addc_co_u32_e32 v149, vcc, 0, v149, vcc
	v_cvt_pk_bf16_f32 v153, v168, v169
	global_store_dwordx4 v[148:149], v[150:153], off nt
	v_pk_mul_f32 v[148:149], v[14:15], v[164:165] op_sel_hi:[1,0]
	s_nop 0
	v_pk_mul_f32 v[150:151], v[12:13], v[164:165] op_sel_hi:[1,0]
	v_pk_mul_f32 v[152:153], v[10:11], v[164:165] op_sel_hi:[1,0]
	v_pk_mul_f32 v[164:165], v[8:9], v[164:165] op_sel_hi:[1,0]
	v_max_f32_e32 v150, 0, v150
	v_max_f32_e32 v164, 0, v164
	v_max_f32_e32 v151, 0, v151
	v_max_f32_e32 v165, 0, v165
	v_max_f32_e32 v148, 0, v148
	v_max_f32_e32 v149, 0, v149
	v_max_f32_e32 v152, 0, v152
	v_max_f32_e32 v153, 0, v153
	v_pk_mul_f32 v[168:169], v[148:149], v[148:149]
	v_pk_mul_f32 v[148:149], v[150:151], v[150:151]
	v_pk_mul_f32 v[150:151], v[164:165], v[164:165]
	v_pk_mul_f32 v[152:153], v[152:153], v[152:153]
	v_cvt_pk_bf16_f32 v148, v148, v149
	v_cvt_pk_bf16_f32 v149, v168, v169
	v_cvt_pk_bf16_f32 v150, v150, v151
	s_nop 0
	v_cvt_pk_bf16_f32 v151, v152, v153
	global_store_dwordx4 v[166:167], v[148:151], off offset:256 nt
	s_cbranch_execz .LBB0_2293
